# V^T epilogue of the int8 w_in tiles: lane-pair exchange (dpp+perm) and one dword store instead of two short stores
# baseline (speedup 1.0000x reference)
.LBB0_845:
	s_andn2_b64 vcc, exec, s[0:1]
	s_cbranch_vccnz .LBB0_1010
	s_lshl_b32 s17, s35, 1
	s_and_b32 s33, s14, -16
	s_or_b32 s2, s17, s33
	v_ashrrev_i32_e32 v130, 5, v136
	s_ashr_i32 s3, s2, 31
	s_lshl_b32 s0, s5, 10
	v_and_b32_e32 v137, 31, v160
	v_ashrrev_i32_e32 v131, 31, v130
	s_lshl_b64 s[38:39], s[2:3], 14
	v_lshlrev_b64 v[132:133], 13, v[130:131]
	s_or_b32 s38, s38, s0
	v_ashrrev_i32_e32 v135, 31, v134
	s_mov_b64 s[2:3], -1
	s_and_b64 vcc, exec, s[62:63]
	v_lshlrev_b32_e32 v154, 1, v137
	v_and_b32_e32 v204, 1, v137
	v_mul_u32_u24_e32 v200, 62, v204
	v_add_u32_e32 v200, v200, v154
	v_mov_b32_e32 v201, 0
	v_mov_b32_e32 v203, 0xfdfe0606
	v_mul_lo_u32 v204, v204, v203
	v_add_u32_e32 v202, 0x5040100, v204
	s_cbranch_vccz .LBB0_848
	v_lshl_add_u64 v[130:131], s[38:39], 0, v[134:135]
	v_readlane_b32 s2, v254, 63
	v_lshlrev_b64 v[130:131], 6, v[130:131]
	v_readlane_b32 s3, v255, 0
	v_cvt_pk_bf16_f32 v137, v126, v127
	s_movk_i32 s1, 0x2000
	s_nop 0
	v_lshl_add_u64 v[130:131], s[2:3], 0, v[130:131]
	v_lshl_add_u64 v[130:131], v[130:131], 0, v[200:201]
	v_lshl_add_u64 v[130:131], v[130:131], 0, v[132:133]
	s_nop 1
	v_mov_b32_dpp v205, v137 quad_perm:[1,0,3,2] row_mask:0xf bank_mask:0xf
	v_perm_b32 v205, v205, v137, v202
	global_store_dword v[130:131], v205, off
	v_cvt_pk_bf16_f32 v137, v110, v111
	v_add_co_u32_e32 v138, vcc, s1, v130
	s_nop 1
	v_mov_b32_dpp v205, v137 quad_perm:[1,0,3,2] row_mask:0xf bank_mask:0xf
	v_perm_b32 v205, v205, v137, v202
	global_store_dword v[130:131], v205, off offset:32
	v_cvt_pk_bf16_f32 v137, v94, v95
	v_addc_co_u32_e32 v139, vcc, 0, v131, vcc
	s_nop 1
	v_mov_b32_dpp v205, v137 quad_perm:[1,0,3,2] row_mask:0xf bank_mask:0xf
	v_perm_b32 v205, v205, v137, v202
	global_store_dword v[138:139], v205, off
	v_cvt_pk_bf16_f32 v137, v78, v79
	s_mov_b32 s1, 0x8000
	s_nop 1
	v_mov_b32_dpp v205, v137 quad_perm:[1,0,3,2] row_mask:0xf bank_mask:0xf
	v_perm_b32 v205, v205, v137, v202
	global_store_dword v[138:139], v205, off offset:32
	v_add_co_u32_e32 v138, vcc, s1, v130
	v_cvt_pk_bf16_f32 v137, v62, v63
	s_mov_b64 s[2:3], 0
	s_nop 0
	v_addc_co_u32_e32 v139, vcc, 0, v131, vcc
	s_nop 1
	v_mov_b32_dpp v205, v137 quad_perm:[1,0,3,2] row_mask:0xf bank_mask:0xf
	v_perm_b32 v205, v205, v137, v202
	global_store_dword v[138:139], v205, off
	v_cvt_pk_bf16_f32 v137, v46, v47
	v_add_co_u32_e32 v130, vcc, 0xa000, v130
	s_nop 1
	v_mov_b32_dpp v205, v137 quad_perm:[1,0,3,2] row_mask:0xf bank_mask:0xf
	v_perm_b32 v205, v205, v137, v202
	global_store_dword v[138:139], v205, off offset:32
	v_cvt_pk_bf16_f32 v137, v30, v31
	v_addc_co_u32_e32 v131, vcc, 0, v131, vcc
	s_nop 1
	v_mov_b32_dpp v205, v137 quad_perm:[1,0,3,2] row_mask:0xf bank_mask:0xf
	v_perm_b32 v205, v205, v137, v202
	global_store_dword v[130:131], v205, off
	v_cvt_pk_bf16_f32 v137, v10, v11
	s_nop 1
	v_mov_b32_dpp v205, v137 quad_perm:[1,0,3,2] row_mask:0xf bank_mask:0xf
	v_perm_b32 v205, v205, v137, v202
	global_store_dword v[130:131], v205, off offset:32

.LBB0_850:
	v_or_b32_e32 v162, 2, v134
	v_cndmask_b32_e64 v131, 0, 1, s[62:63]
	s_mov_b64 s[42:43], -1
	v_cmp_ne_u32_e64 s[2:3], 1, v131
	s_andn2_b64 vcc, exec, s[62:63]
	v_ashrrev_i32_e32 v163, 31, v162
	s_cbranch_vccnz .LBB0_852
	v_lshl_add_u64 v[140:141], s[38:39], 0, v[162:163]
	v_readlane_b32 s36, v254, 63
	v_lshlrev_b64 v[140:141], 6, v[140:141]
	v_readlane_b32 s37, v255, 0
	v_cvt_pk_bf16_f32 v131, v128, v129
	s_movk_i32 s1, 0x2000
	s_mov_b64 s[42:43], 0
	v_lshl_add_u64 v[140:141], s[36:37], 0, v[140:141]
	v_lshl_add_u64 v[140:141], v[140:141], 0, v[200:201]
	v_lshl_add_u64 v[140:141], v[140:141], 0, v[132:133]
	s_nop 1
	v_mov_b32_dpp v205, v131 quad_perm:[1,0,3,2] row_mask:0xf bank_mask:0xf
	v_perm_b32 v205, v205, v131, v202
	global_store_dword v[140:141], v205, off
	v_cvt_pk_bf16_f32 v131, v112, v113
	v_add_co_u32_e32 v142, vcc, s1, v140
	s_nop 1
	v_mov_b32_dpp v205, v131 quad_perm:[1,0,3,2] row_mask:0xf bank_mask:0xf
	v_perm_b32 v205, v205, v131, v202
	global_store_dword v[140:141], v205, off offset:32
	v_cvt_pk_bf16_f32 v131, v96, v97
	v_addc_co_u32_e32 v143, vcc, 0, v141, vcc
	s_nop 1
	v_mov_b32_dpp v205, v131 quad_perm:[1,0,3,2] row_mask:0xf bank_mask:0xf
	v_perm_b32 v205, v205, v131, v202
	global_store_dword v[142:143], v205, off
	v_cvt_pk_bf16_f32 v131, v80, v81
	s_mov_b32 s1, 0x8000
	s_nop 1
	v_mov_b32_dpp v205, v131 quad_perm:[1,0,3,2] row_mask:0xf bank_mask:0xf
	v_perm_b32 v205, v205, v131, v202
	global_store_dword v[142:143], v205, off offset:32
	v_add_co_u32_e32 v142, vcc, s1, v140
	v_cvt_pk_bf16_f32 v131, v64, v65
	s_nop 1
	v_addc_co_u32_e32 v143, vcc, 0, v141, vcc
	s_nop 1
	v_mov_b32_dpp v205, v131 quad_perm:[1,0,3,2] row_mask:0xf bank_mask:0xf
	v_perm_b32 v205, v205, v131, v202
	global_store_dword v[142:143], v205, off
	v_cvt_pk_bf16_f32 v131, v48, v49
	v_add_co_u32_e32 v140, vcc, 0xa000, v140
	s_nop 1
	v_mov_b32_dpp v205, v131 quad_perm:[1,0,3,2] row_mask:0xf bank_mask:0xf
	v_perm_b32 v205, v205, v131, v202
	global_store_dword v[142:143], v205, off offset:32
	v_cvt_pk_bf16_f32 v131, v32, v33
	v_addc_co_u32_e32 v141, vcc, 0, v141, vcc
	s_nop 1
	v_mov_b32_dpp v205, v131 quad_perm:[1,0,3,2] row_mask:0xf bank_mask:0xf
	v_perm_b32 v205, v205, v131, v202
	global_store_dword v[140:141], v205, off
	v_cvt_pk_bf16_f32 v131, v12, v13
	s_nop 1
	v_mov_b32_dpp v205, v131 quad_perm:[1,0,3,2] row_mask:0xf bank_mask:0xf
	v_perm_b32 v205, v205, v131, v202
	global_store_dword v[140:141], v205, off offset:32

.LBB0_854:
	v_or_b32_e32 v164, 4, v134
	s_mov_b64 s[42:43], -1
	s_and_b64 vcc, exec, s[2:3]
	v_ashrrev_i32_e32 v165, 31, v164
	s_cbranch_vccnz .LBB0_856
	v_lshl_add_u64 v[142:143], s[38:39], 0, v[164:165]
	v_readlane_b32 s36, v254, 63
	v_lshlrev_b64 v[142:143], 6, v[142:143]
	v_readlane_b32 s37, v255, 0
	v_cvt_pk_bf16_f32 v131, v122, v123
	s_movk_i32 s1, 0x2000
	s_mov_b64 s[42:43], 0
	v_lshl_add_u64 v[142:143], s[36:37], 0, v[142:143]
	v_lshl_add_u64 v[142:143], v[142:143], 0, v[200:201]
	v_lshl_add_u64 v[142:143], v[142:143], 0, v[132:133]
	s_nop 1
	v_mov_b32_dpp v205, v131 quad_perm:[1,0,3,2] row_mask:0xf bank_mask:0xf
	v_perm_b32 v205, v205, v131, v202
	global_store_dword v[142:143], v205, off
	v_cvt_pk_bf16_f32 v131, v106, v107
	v_add_co_u32_e32 v144, vcc, s1, v142
	s_nop 1
	v_mov_b32_dpp v205, v131 quad_perm:[1,0,3,2] row_mask:0xf bank_mask:0xf
	v_perm_b32 v205, v205, v131, v202
	global_store_dword v[142:143], v205, off offset:32
	v_cvt_pk_bf16_f32 v131, v90, v91
	v_addc_co_u32_e32 v145, vcc, 0, v143, vcc
	s_nop 1
	v_mov_b32_dpp v205, v131 quad_perm:[1,0,3,2] row_mask:0xf bank_mask:0xf
	v_perm_b32 v205, v205, v131, v202
	global_store_dword v[144:145], v205, off
	v_cvt_pk_bf16_f32 v131, v74, v75
	s_mov_b32 s1, 0x8000
	s_nop 1
	v_mov_b32_dpp v205, v131 quad_perm:[1,0,3,2] row_mask:0xf bank_mask:0xf
	v_perm_b32 v205, v205, v131, v202
	global_store_dword v[144:145], v205, off offset:32
	v_add_co_u32_e32 v144, vcc, s1, v142
	v_cvt_pk_bf16_f32 v131, v58, v59
	s_nop 1
	v_addc_co_u32_e32 v145, vcc, 0, v143, vcc
	s_nop 1
	v_mov_b32_dpp v205, v131 quad_perm:[1,0,3,2] row_mask:0xf bank_mask:0xf
	v_perm_b32 v205, v205, v131, v202
	global_store_dword v[144:145], v205, off
	v_cvt_pk_bf16_f32 v131, v42, v43
	v_add_co_u32_e32 v142, vcc, 0xa000, v142
	s_nop 1
	v_mov_b32_dpp v205, v131 quad_perm:[1,0,3,2] row_mask:0xf bank_mask:0xf
	v_perm_b32 v205, v205, v131, v202
	global_store_dword v[144:145], v205, off offset:32
	v_cvt_pk_bf16_f32 v131, v26, v27
	v_addc_co_u32_e32 v143, vcc, 0, v143, vcc
	s_nop 1
	v_mov_b32_dpp v205, v131 quad_perm:[1,0,3,2] row_mask:0xf bank_mask:0xf
	v_perm_b32 v205, v205, v131, v202
	global_store_dword v[142:143], v205, off
	v_cvt_pk_bf16_f32 v131, v14, v15
	s_nop 1
	v_mov_b32_dpp v205, v131 quad_perm:[1,0,3,2] row_mask:0xf bank_mask:0xf
	v_perm_b32 v205, v205, v131, v202
	global_store_dword v[142:143], v205, off offset:32

.LBB0_858:
	v_or_b32_e32 v166, 6, v134
	s_mov_b64 s[42:43], -1
	s_and_b64 vcc, exec, s[2:3]
	v_ashrrev_i32_e32 v167, 31, v166
	s_cbranch_vccnz .LBB0_860
	v_lshl_add_u64 v[144:145], s[38:39], 0, v[166:167]
	v_readlane_b32 s36, v254, 63
	v_lshlrev_b64 v[144:145], 6, v[144:145]
	v_readlane_b32 s37, v255, 0
	v_cvt_pk_bf16_f32 v131, v124, v125
	s_movk_i32 s1, 0x2000
	s_mov_b64 s[42:43], 0
	v_lshl_add_u64 v[144:145], s[36:37], 0, v[144:145]
	v_lshl_add_u64 v[144:145], v[144:145], 0, v[200:201]
	v_lshl_add_u64 v[144:145], v[144:145], 0, v[132:133]
	s_nop 1
	v_mov_b32_dpp v205, v131 quad_perm:[1,0,3,2] row_mask:0xf bank_mask:0xf
	v_perm_b32 v205, v205, v131, v202
	global_store_dword v[144:145], v205, off
	v_cvt_pk_bf16_f32 v131, v108, v109
	v_add_co_u32_e32 v184, vcc, s1, v144
	s_nop 1
	v_mov_b32_dpp v205, v131 quad_perm:[1,0,3,2] row_mask:0xf bank_mask:0xf
	v_perm_b32 v205, v205, v131, v202
	global_store_dword v[144:145], v205, off offset:32
	v_cvt_pk_bf16_f32 v131, v92, v93
	v_addc_co_u32_e32 v185, vcc, 0, v145, vcc
	s_nop 1
	v_mov_b32_dpp v205, v131 quad_perm:[1,0,3,2] row_mask:0xf bank_mask:0xf
	v_perm_b32 v205, v205, v131, v202
	global_store_dword v[184:185], v205, off
	v_cvt_pk_bf16_f32 v131, v76, v77
	s_mov_b32 s1, 0x8000
	s_nop 1
	v_mov_b32_dpp v205, v131 quad_perm:[1,0,3,2] row_mask:0xf bank_mask:0xf
	v_perm_b32 v205, v205, v131, v202
	global_store_dword v[184:185], v205, off offset:32
	v_add_co_u32_e32 v184, vcc, s1, v144
	v_cvt_pk_bf16_f32 v131, v60, v61
	s_nop 1
	v_addc_co_u32_e32 v185, vcc, 0, v145, vcc
	s_nop 1
	v_mov_b32_dpp v205, v131 quad_perm:[1,0,3,2] row_mask:0xf bank_mask:0xf
	v_perm_b32 v205, v205, v131, v202
	global_store_dword v[184:185], v205, off
	v_cvt_pk_bf16_f32 v131, v44, v45
	v_add_co_u32_e32 v144, vcc, 0xa000, v144
	s_nop 1
	v_mov_b32_dpp v205, v131 quad_perm:[1,0,3,2] row_mask:0xf bank_mask:0xf
	v_perm_b32 v205, v205, v131, v202
	global_store_dword v[184:185], v205, off offset:32
	v_cvt_pk_bf16_f32 v131, v28, v29
	v_addc_co_u32_e32 v145, vcc, 0, v145, vcc
	s_nop 1
	v_mov_b32_dpp v205, v131 quad_perm:[1,0,3,2] row_mask:0xf bank_mask:0xf
	v_perm_b32 v205, v205, v131, v202
	global_store_dword v[144:145], v205, off
	v_cvt_pk_bf16_f32 v131, v16, v17
	s_nop 1
	v_mov_b32_dpp v205, v131 quad_perm:[1,0,3,2] row_mask:0xf bank_mask:0xf
	v_perm_b32 v205, v205, v131, v202
	global_store_dword v[144:145], v205, off offset:32

.LBB0_862:
	s_or_b32 s17, s17, 1
	s_or_b32 s38, s17, s33
	s_ashr_i32 s39, s38, 31
	s_mov_b32 s1, s7
	s_lshl_b64 s[38:39], s[38:39], 14
	s_or_b64 s[0:1], s[38:39], s[0:1]
	s_and_b64 vcc, exec, s[2:3]
	s_mov_b64 s[38:39], -1
	s_cbranch_vccnz .LBB0_1000
	v_lshl_add_u64 v[184:185], s[0:1], 0, v[134:135]
	v_readlane_b32 s36, v254, 63
	v_lshlrev_b64 v[184:185], 6, v[184:185]
	v_readlane_b32 s37, v255, 0
	v_cvt_pk_bf16_f32 v131, v118, v119
	s_movk_i32 s15, 0x2000
	s_nop 0
	v_lshl_add_u64 v[184:185], s[36:37], 0, v[184:185]
	v_lshl_add_u64 v[184:185], v[184:185], 0, v[200:201]
	v_lshl_add_u64 v[184:185], v[184:185], 0, v[132:133]
	s_nop 1
	v_mov_b32_dpp v205, v131 quad_perm:[1,0,3,2] row_mask:0xf bank_mask:0xf
	v_perm_b32 v205, v205, v131, v202
	global_store_dword v[184:185], v205, off
	v_cvt_pk_bf16_f32 v131, v102, v103
	v_add_co_u32_e32 v186, vcc, s15, v184
	s_nop 1
	v_mov_b32_dpp v205, v131 quad_perm:[1,0,3,2] row_mask:0xf bank_mask:0xf
	v_perm_b32 v205, v205, v131, v202
	global_store_dword v[184:185], v205, off offset:32
	v_cvt_pk_bf16_f32 v131, v86, v87
	v_addc_co_u32_e32 v187, vcc, 0, v185, vcc
	s_nop 1
	v_mov_b32_dpp v205, v131 quad_perm:[1,0,3,2] row_mask:0xf bank_mask:0xf
	v_perm_b32 v205, v205, v131, v202
	global_store_dword v[186:187], v205, off
	v_cvt_pk_bf16_f32 v131, v70, v71
	s_mov_b32 s15, 0x8000
	s_nop 1
	v_mov_b32_dpp v205, v131 quad_perm:[1,0,3,2] row_mask:0xf bank_mask:0xf
	v_perm_b32 v205, v205, v131, v202
	global_store_dword v[186:187], v205, off offset:32
	v_add_co_u32_e32 v186, vcc, s15, v184
	v_cvt_pk_bf16_f32 v131, v54, v55
	s_nop 1
	v_addc_co_u32_e32 v187, vcc, 0, v185, vcc
	s_nop 1
	v_mov_b32_dpp v205, v131 quad_perm:[1,0,3,2] row_mask:0xf bank_mask:0xf
	v_perm_b32 v205, v205, v131, v202
	global_store_dword v[186:187], v205, off
	v_cvt_pk_bf16_f32 v131, v38, v39
	v_add_co_u32_e32 v184, vcc, 0xa000, v184
	s_nop 1
	v_mov_b32_dpp v205, v131 quad_perm:[1,0,3,2] row_mask:0xf bank_mask:0xf
	v_perm_b32 v205, v205, v131, v202
	global_store_dword v[186:187], v205, off offset:32
	v_cvt_pk_bf16_f32 v131, v22, v23
	v_addc_co_u32_e32 v185, vcc, 0, v185, vcc
	s_nop 1
	v_mov_b32_dpp v205, v131 quad_perm:[1,0,3,2] row_mask:0xf bank_mask:0xf
	v_perm_b32 v205, v205, v131, v202
	global_store_dword v[184:185], v205, off
	v_cvt_pk_bf16_f32 v131, v2, v3
	s_nop 1
	v_mov_b32_dpp v205, v131 quad_perm:[1,0,3,2] row_mask:0xf bank_mask:0xf
	v_perm_b32 v205, v205, v131, v202
	global_store_dword v[184:185], v205, off offset:32
	v_and_or_b32 v182, v182, -16, s17
	s_cbranch_execz .LBB0_1001

.LBB0_865:
	v_lshl_add_u64 v[138:139], s[0:1], 0, v[162:163]
	v_readlane_b32 s36, v254, 63
	v_lshlrev_b64 v[138:139], 6, v[138:139]
	v_readlane_b32 s37, v255, 0
	v_cvt_pk_bf16_f32 v131, v120, v121
	s_movk_i32 s15, 0x2000
	s_nop 0
	v_lshl_add_u64 v[138:139], s[36:37], 0, v[138:139]
	v_lshl_add_u64 v[138:139], v[138:139], 0, v[200:201]
	v_lshl_add_u64 v[138:139], v[138:139], 0, v[132:133]
	s_nop 1
	v_mov_b32_dpp v205, v131 quad_perm:[1,0,3,2] row_mask:0xf bank_mask:0xf
	v_perm_b32 v205, v205, v131, v202
	global_store_dword v[138:139], v205, off
	v_cvt_pk_bf16_f32 v131, v104, v105
	v_add_co_u32_e32 v162, vcc, s15, v138
	s_nop 1
	v_mov_b32_dpp v205, v131 quad_perm:[1,0,3,2] row_mask:0xf bank_mask:0xf
	v_perm_b32 v205, v205, v131, v202
	global_store_dword v[138:139], v205, off offset:32
	v_cvt_pk_bf16_f32 v131, v88, v89
	v_addc_co_u32_e32 v163, vcc, 0, v139, vcc
	s_nop 1
	v_mov_b32_dpp v205, v131 quad_perm:[1,0,3,2] row_mask:0xf bank_mask:0xf
	v_perm_b32 v205, v205, v131, v202
	global_store_dword v[162:163], v205, off
	v_cvt_pk_bf16_f32 v131, v72, v73
	s_mov_b32 s15, 0x8000
	s_nop 1
	v_mov_b32_dpp v205, v131 quad_perm:[1,0,3,2] row_mask:0xf bank_mask:0xf
	v_perm_b32 v205, v205, v131, v202
	global_store_dword v[162:163], v205, off offset:32
	v_add_co_u32_e32 v162, vcc, s15, v138
	v_cvt_pk_bf16_f32 v131, v56, v57
	s_nop 1
	v_addc_co_u32_e32 v163, vcc, 0, v139, vcc
	s_nop 1
	v_mov_b32_dpp v205, v131 quad_perm:[1,0,3,2] row_mask:0xf bank_mask:0xf
	v_perm_b32 v205, v205, v131, v202
	global_store_dword v[162:163], v205, off
	v_cvt_pk_bf16_f32 v131, v40, v41
	v_add_co_u32_e32 v138, vcc, 0xa000, v138
	s_nop 1
	v_mov_b32_dpp v205, v131 quad_perm:[1,0,3,2] row_mask:0xf bank_mask:0xf
	v_perm_b32 v205, v205, v131, v202
	global_store_dword v[162:163], v205, off offset:32
	v_cvt_pk_bf16_f32 v131, v24, v25
	v_addc_co_u32_e32 v139, vcc, 0, v139, vcc
	s_nop 1
	v_mov_b32_dpp v205, v131 quad_perm:[1,0,3,2] row_mask:0xf bank_mask:0xf
	v_perm_b32 v205, v205, v131, v202
	global_store_dword v[138:139], v205, off
	v_cvt_pk_bf16_f32 v131, v4, v5
	s_nop 1
	v_mov_b32_dpp v205, v131 quad_perm:[1,0,3,2] row_mask:0xf bank_mask:0xf
	v_perm_b32 v205, v205, v131, v202
	global_store_dword v[138:139], v205, off offset:32
	s_cbranch_execz .LBB0_1003

.LBB0_867:
	v_lshl_add_u64 v[138:139], s[0:1], 0, v[164:165]
	v_readlane_b32 s36, v254, 63
	v_lshlrev_b64 v[138:139], 6, v[138:139]
	v_readlane_b32 s37, v255, 0
	v_cvt_pk_bf16_f32 v131, v114, v115
	s_movk_i32 s15, 0x2000
	s_nop 0
	v_lshl_add_u64 v[138:139], s[36:37], 0, v[138:139]
	v_lshl_add_u64 v[138:139], v[138:139], 0, v[200:201]
	v_lshl_add_u64 v[138:139], v[138:139], 0, v[132:133]
	s_nop 1
	v_mov_b32_dpp v205, v131 quad_perm:[1,0,3,2] row_mask:0xf bank_mask:0xf
	v_perm_b32 v205, v205, v131, v202
	global_store_dword v[138:139], v205, off
	v_cvt_pk_bf16_f32 v131, v98, v99
	v_add_co_u32_e32 v140, vcc, s15, v138
	s_nop 1
	v_mov_b32_dpp v205, v131 quad_perm:[1,0,3,2] row_mask:0xf bank_mask:0xf
	v_perm_b32 v205, v205, v131, v202
	global_store_dword v[138:139], v205, off offset:32
	v_cvt_pk_bf16_f32 v131, v82, v83
	v_addc_co_u32_e32 v141, vcc, 0, v139, vcc
	s_nop 1
	v_mov_b32_dpp v205, v131 quad_perm:[1,0,3,2] row_mask:0xf bank_mask:0xf
	v_perm_b32 v205, v205, v131, v202
	global_store_dword v[140:141], v205, off
	v_cvt_pk_bf16_f32 v131, v66, v67
	s_mov_b32 s15, 0x8000
	s_nop 1
	v_mov_b32_dpp v205, v131 quad_perm:[1,0,3,2] row_mask:0xf bank_mask:0xf
	v_perm_b32 v205, v205, v131, v202
	global_store_dword v[140:141], v205, off offset:32
	v_add_co_u32_e32 v140, vcc, s15, v138
	v_cvt_pk_bf16_f32 v131, v50, v51
	s_nop 1
	v_addc_co_u32_e32 v141, vcc, 0, v139, vcc
	s_nop 1
	v_mov_b32_dpp v205, v131 quad_perm:[1,0,3,2] row_mask:0xf bank_mask:0xf
	v_perm_b32 v205, v205, v131, v202
	global_store_dword v[140:141], v205, off
	v_cvt_pk_bf16_f32 v131, v34, v35
	v_add_co_u32_e32 v138, vcc, 0xa000, v138
	s_nop 1
	v_mov_b32_dpp v205, v131 quad_perm:[1,0,3,2] row_mask:0xf bank_mask:0xf
	v_perm_b32 v205, v205, v131, v202
	global_store_dword v[140:141], v205, off offset:32
	v_cvt_pk_bf16_f32 v131, v18, v19
	v_addc_co_u32_e32 v139, vcc, 0, v139, vcc
	s_nop 1
	v_mov_b32_dpp v205, v131 quad_perm:[1,0,3,2] row_mask:0xf bank_mask:0xf
	v_perm_b32 v205, v205, v131, v202
	global_store_dword v[138:139], v205, off
	v_cvt_pk_bf16_f32 v131, v6, v7
	s_nop 1
	v_mov_b32_dpp v205, v131 quad_perm:[1,0,3,2] row_mask:0xf bank_mask:0xf
	v_perm_b32 v205, v205, v131, v202
	global_store_dword v[138:139], v205, off offset:32
	s_cbranch_execz .LBB0_1005

.LBB0_869:
	v_lshl_add_u64 v[138:139], s[0:1], 0, v[166:167]
	v_readlane_b32 s0, v254, 63
	v_lshlrev_b64 v[138:139], 6, v[138:139]
	v_readlane_b32 s1, v255, 0
	v_cvt_pk_bf16_f32 v131, v116, v117
	s_nop 1
	v_lshl_add_u64 v[138:139], s[0:1], 0, v[138:139]
	v_lshl_add_u64 v[138:139], v[138:139], 0, v[200:201]
	v_lshl_add_u64 v[132:133], v[138:139], 0, v[132:133]
	s_movk_i32 s0, 0x2000
	s_nop 1
	v_mov_b32_dpp v205, v131 quad_perm:[1,0,3,2] row_mask:0xf bank_mask:0xf
	v_perm_b32 v205, v205, v131, v202
	global_store_dword v[132:133], v205, off
	v_cvt_pk_bf16_f32 v131, v100, v101
	v_add_co_u32_e32 v138, vcc, s0, v132
	s_nop 1
	v_mov_b32_dpp v205, v131 quad_perm:[1,0,3,2] row_mask:0xf bank_mask:0xf
	v_perm_b32 v205, v205, v131, v202
	global_store_dword v[132:133], v205, off offset:32
	v_cvt_pk_bf16_f32 v131, v84, v85
	v_addc_co_u32_e32 v139, vcc, 0, v133, vcc
	s_nop 1
	v_mov_b32_dpp v205, v131 quad_perm:[1,0,3,2] row_mask:0xf bank_mask:0xf
	v_perm_b32 v205, v205, v131, v202
	global_store_dword v[138:139], v205, off
	v_cvt_pk_bf16_f32 v131, v68, v69
	s_mov_b32 s0, 0x8000
	s_nop 1
	v_mov_b32_dpp v205, v131 quad_perm:[1,0,3,2] row_mask:0xf bank_mask:0xf
	v_perm_b32 v205, v205, v131, v202
	global_store_dword v[138:139], v205, off offset:32
	v_add_co_u32_e32 v138, vcc, s0, v132
	v_cvt_pk_bf16_f32 v131, v52, v53
	s_nop 1
	v_addc_co_u32_e32 v139, vcc, 0, v133, vcc
	s_nop 1
	v_mov_b32_dpp v205, v131 quad_perm:[1,0,3,2] row_mask:0xf bank_mask:0xf
	v_perm_b32 v205, v205, v131, v202
	global_store_dword v[138:139], v205, off
	v_cvt_pk_bf16_f32 v131, v36, v37
	v_add_co_u32_e32 v132, vcc, 0xa000, v132
	s_nop 1
	v_mov_b32_dpp v205, v131 quad_perm:[1,0,3,2] row_mask:0xf bank_mask:0xf
	v_perm_b32 v205, v205, v131, v202
	global_store_dword v[138:139], v205, off offset:32
	v_cvt_pk_bf16_f32 v131, v20, v21
	v_addc_co_u32_e32 v133, vcc, 0, v133, vcc
	s_nop 1
	v_mov_b32_dpp v205, v131 quad_perm:[1,0,3,2] row_mask:0xf bank_mask:0xf
	v_perm_b32 v205, v205, v131, v202
	global_store_dword v[132:133], v205, off
	v_cvt_pk_bf16_f32 v131, v8, v9
	s_nop 1
	v_mov_b32_dpp v205, v131 quad_perm:[1,0,3,2] row_mask:0xf bank_mask:0xf
	v_perm_b32 v205, v205, v131, v202
	global_store_dword v[132:133], v205, off offset:32
	s_cbranch_execz .LBB0_1007
	s_branch .LBB0_1008
